# retention state update: LDS transposed reads software-pipelined one k-step ahead (alternating fragment register sets, counted lgkmcnt) instead of read-all/wait/MFMA per step
# baseline (speedup 1.0000x reference)
.LBB0_130:
	s_and_b64 s[12:13], s[6:7], s[12:13]
	s_and_b64 vcc, exec, s[12:13]
	s_cbranch_vccnz .LBB0_132
	ds_read_b64_tr_b16 v[104:105], v229
	ds_read_b64_tr_b16 v[108:109], v229 offset:32
	ds_read_b64_tr_b16 v[112:113], v229 offset:64
	ds_read_b64_tr_b16 v[116:117], v229 offset:96
	ds_read_b64_tr_b16 v[106:107], v229 offset:2560
	ds_read_b64_tr_b16 v[110:111], v229 offset:2592
	ds_read_b64_tr_b16 v[114:115], v229 offset:2624
	ds_read_b64_tr_b16 v[118:119], v229 offset:2656
	v_add_u32_e32 v126, s38, v210
	ds_read_b64_tr_b16 v[120:121], v126
	ds_read_b64_tr_b16 v[122:123], v126 offset:8704
	ds_read_b64_tr_b16 v[124:125], v126 offset:32
	ds_read_b64_tr_b16 v[126:127], v126 offset:8736
	v_mov_b32_e32 v161, v160
	v_pk_mul_f32 v[102:103], v[160:161], v[102:103]
	v_pk_mul_f32 v[100:101], v[170:171], v[100:101]
	v_pk_mul_f32 v[98:99], v[160:161], v[98:99]
	v_pk_mul_f32 v[96:97], v[170:171], v[96:97]
	v_pk_mul_f32 v[94:95], v[160:161], v[94:95]
	v_pk_mul_f32 v[92:93], v[170:171], v[92:93]
	v_pk_mul_f32 v[90:91], v[160:161], v[90:91]
	v_pk_mul_f32 v[88:89], v[170:171], v[88:89]
	v_pk_mul_f32 v[86:87], v[160:161], v[86:87]
	v_pk_mul_f32 v[84:85], v[170:171], v[84:85]
	v_pk_mul_f32 v[82:83], v[160:161], v[82:83]
	v_pk_mul_f32 v[80:81], v[170:171], v[80:81]
	v_pk_mul_f32 v[78:79], v[160:161], v[78:79]
	v_pk_mul_f32 v[76:77], v[170:171], v[76:77]
	v_pk_mul_f32 v[74:75], v[160:161], v[74:75]
	v_pk_mul_f32 v[72:73], v[170:171], v[72:73]
	s_waitcnt lgkmcnt(2)
	v_mfma_f32_16x16x32_bf16 v[100:103], v[104:107], v[120:123], v[100:103]
	v_mfma_f32_16x16x32_bf16 v[96:99], v[108:111], v[120:123], v[96:99]
	v_mfma_f32_16x16x32_bf16 v[92:95], v[112:115], v[120:123], v[92:95]
	v_mfma_f32_16x16x32_bf16 v[88:91], v[116:119], v[120:123], v[88:91]
	ds_read_b64_tr_b16 v[128:129], v230
	ds_read_b64_tr_b16 v[132:133], v230 offset:32
	ds_read_b64_tr_b16 v[136:137], v230 offset:64
	ds_read_b64_tr_b16 v[140:141], v230 offset:96
	ds_read_b64_tr_b16 v[130:131], v230 offset:2560
	ds_read_b64_tr_b16 v[134:135], v230 offset:2592
	ds_read_b64_tr_b16 v[138:139], v230 offset:2624
	ds_read_b64_tr_b16 v[142:143], v230 offset:2656
	ds_read_b64_tr_b16 v[172:173], v231
	ds_read_b64_tr_b16 v[174:175], v231 offset:8704
	s_waitcnt lgkmcnt(10)
	v_mfma_f32_16x16x32_bf16 v[84:87], v[104:107], v[124:127], v[84:87]
	v_mfma_f32_16x16x32_bf16 v[80:83], v[108:111], v[124:127], v[80:83]
	v_mfma_f32_16x16x32_bf16 v[76:79], v[112:115], v[124:127], v[76:79]
	v_mfma_f32_16x16x32_bf16 v[72:75], v[116:119], v[124:127], v[72:75]
	ds_read_b64_tr_b16 v[124:125], v231 offset:32
	ds_read_b64_tr_b16 v[126:127], v231 offset:8736
	s_waitcnt lgkmcnt(2)
	v_mfma_f32_16x16x32_bf16 v[100:103], v[128:131], v[172:175], v[100:103]
	v_mfma_f32_16x16x32_bf16 v[96:99], v[132:135], v[172:175], v[96:99]
	v_mfma_f32_16x16x32_bf16 v[92:95], v[136:139], v[172:175], v[92:95]
	v_mfma_f32_16x16x32_bf16 v[88:91], v[140:143], v[172:175], v[88:91]
	ds_read_b64_tr_b16 v[104:105], v232
	ds_read_b64_tr_b16 v[108:109], v232 offset:32
	ds_read_b64_tr_b16 v[112:113], v232 offset:64
	ds_read_b64_tr_b16 v[116:117], v232 offset:96
	ds_read_b64_tr_b16 v[106:107], v232 offset:2560
	ds_read_b64_tr_b16 v[110:111], v232 offset:2592
	ds_read_b64_tr_b16 v[114:115], v232 offset:2624
	ds_read_b64_tr_b16 v[118:119], v232 offset:2656
	ds_read_b64_tr_b16 v[120:121], v233
	ds_read_b64_tr_b16 v[122:123], v233 offset:8704
	s_waitcnt lgkmcnt(10)
	v_mfma_f32_16x16x32_bf16 v[84:87], v[128:131], v[124:127], v[84:87]
	v_mfma_f32_16x16x32_bf16 v[80:83], v[132:135], v[124:127], v[80:83]
	v_mfma_f32_16x16x32_bf16 v[76:79], v[136:139], v[124:127], v[76:79]
	v_mfma_f32_16x16x32_bf16 v[72:75], v[140:143], v[124:127], v[72:75]
	ds_read_b64_tr_b16 v[124:125], v233 offset:32
	ds_read_b64_tr_b16 v[126:127], v233 offset:8736
	s_waitcnt lgkmcnt(2)
	v_mfma_f32_16x16x32_bf16 v[100:103], v[104:107], v[120:123], v[100:103]
	v_mfma_f32_16x16x32_bf16 v[96:99], v[108:111], v[120:123], v[96:99]
	v_mfma_f32_16x16x32_bf16 v[92:95], v[112:115], v[120:123], v[92:95]
	v_mfma_f32_16x16x32_bf16 v[88:91], v[116:119], v[120:123], v[88:91]
	ds_read_b64_tr_b16 v[128:129], v234
	ds_read_b64_tr_b16 v[132:133], v234 offset:32
	ds_read_b64_tr_b16 v[136:137], v234 offset:64
	ds_read_b64_tr_b16 v[140:141], v234 offset:96
	ds_read_b64_tr_b16 v[130:131], v234 offset:2560
	ds_read_b64_tr_b16 v[134:135], v234 offset:2592
	ds_read_b64_tr_b16 v[138:139], v234 offset:2624
	ds_read_b64_tr_b16 v[142:143], v234 offset:2656
	ds_read_b64_tr_b16 v[172:173], v235
	ds_read_b64_tr_b16 v[174:175], v235 offset:8704
	s_waitcnt lgkmcnt(10)
	v_mfma_f32_16x16x32_bf16 v[84:87], v[104:107], v[124:127], v[84:87]
	v_mfma_f32_16x16x32_bf16 v[80:83], v[108:111], v[124:127], v[80:83]
	v_mfma_f32_16x16x32_bf16 v[76:79], v[112:115], v[124:127], v[76:79]
	v_mfma_f32_16x16x32_bf16 v[72:75], v[116:119], v[124:127], v[72:75]
	ds_read_b64_tr_b16 v[124:125], v235 offset:32
	ds_read_b64_tr_b16 v[126:127], v235 offset:8736
	s_waitcnt lgkmcnt(2)
	v_mfma_f32_16x16x32_bf16 v[100:103], v[128:131], v[172:175], v[100:103]
	v_mfma_f32_16x16x32_bf16 v[96:99], v[132:135], v[172:175], v[96:99]
	v_mfma_f32_16x16x32_bf16 v[92:95], v[136:139], v[172:175], v[92:95]
	v_mfma_f32_16x16x32_bf16 v[88:91], v[140:143], v[172:175], v[88:91]
	s_waitcnt lgkmcnt(0)
	v_mfma_f32_16x16x32_bf16 v[84:87], v[128:131], v[124:127], v[84:87]
	v_mfma_f32_16x16x32_bf16 v[80:83], v[132:135], v[124:127], v[80:83]
	v_mfma_f32_16x16x32_bf16 v[76:79], v[136:139], v[124:127], v[76:79]
	v_mfma_f32_16x16x32_bf16 v[72:75], v[140:143], v[124:127], v[72:75]
